# attention tile: K/V fragment LDS reads of each QK / PV segment issued up front with counted lgkmcnt waits
# baseline (speedup 1.0000x reference)
; __device__ __forceinline__ float fast_exp2(float x) { return __builtin_amdgcn_exp2f(x); }
; __device__ __forceinline__ float fast_rcp(float x) { return __builtin_amdgcn_rcpf(x); }
; template <int NB, bool MASK> __device__ __forceinline__ void sb_transform(f32x16* P, float& R, int hi, int kpos0, int qpos) {
;     float T[NB][4];
; #pragma unroll
;     for (int b = 0; b < NB; ++b)
; #pragma unroll
;         for (int g = 0; g < 4; ++g) {
;             float be[4], f[4];
; #pragma unroll
;             for (int i = 0; i < 4; ++i) {
;                 const float z = fmaxf(P[b][4 * g + i], -100.f);
;                 const float e = fast_exp2(-z), rc = fast_rcp(1.f + e);
;                 be[i] = rc; f[i] = e * rc;
;                 if (MASK) { const bool ok = (kpos0 + 32 * b + 8 * g + 4 * hi + i) < qpos; be[i] = ok ? be[i] : 0.f; f[i] = ok ? f[i] : 1.f; }
;             }
.LBB0_872:
	s_lshl_b32 s87, s86, 14
	v_add_u32_e32 v2, s87, v211
	v_add_u32_e32 v172, v2, v212
	v_add_u32_e32 v174, v2, v213
	v_add_u32_e32 v175, v2, v214
	v_add_u32_e32 v176, v2, v215
	v_add_u32_e32 v177, v2, v216
	v_add_u32_e32 v178, v2, v217
	v_add_u32_e32 v179, v2, v218
	v_add_u32_e32 v180, v2, v219
	ds_read_b128 v[222:225], v172 offset:40960
	ds_read_b128 v[226:229], v174 offset:40960
	ds_read_b128 v[230:233], v175 offset:40960
	ds_read_b128 v[238:241], v176 offset:40960
	ds_read_b128 v[242:245], v177 offset:40960
	ds_read_b128 v[246:249], v178 offset:40960
	ds_read_b128 v[250:253], v179 offset:40960
	ds_read_b128 v[186:189], v180 offset:40960
	s_or_b32 s11, s10, 63
	s_cmp_ge_i32 s11, s78
	s_mov_b64 s[8:9], -1
	s_cselect_b64 s[50:51], -1, 0
	v_or_b32_e32 v2, s10, v210
	s_cmp_lt_i32 s11, s78
	s_waitcnt lgkmcnt(7)
	v_mfma_f32_32x32x16_bf16 v[84:99], v[222:225], v[100:103], v[68:83]
	s_waitcnt lgkmcnt(6)
	v_mfma_f32_32x32x16_bf16 v[84:99], v[226:229], v[104:107], v[84:99]
	s_waitcnt lgkmcnt(5)
	v_mfma_f32_32x32x16_bf16 v[84:99], v[230:233], v[108:111], v[84:99]
	s_waitcnt lgkmcnt(4)
	v_mfma_f32_32x32x16_bf16 v[84:99], v[238:241], v[112:115], v[84:99]
	s_waitcnt lgkmcnt(3)
	v_mfma_f32_32x32x16_bf16 v[84:99], v[242:245], v[116:119], v[84:99]
	s_waitcnt lgkmcnt(2)
	v_mfma_f32_32x32x16_bf16 v[84:99], v[246:249], v[120:123], v[84:99]
	s_waitcnt lgkmcnt(1)
	v_mfma_f32_32x32x16_bf16 v[84:99], v[250:253], v[124:127], v[84:99]
	s_waitcnt lgkmcnt(0)
	v_mfma_f32_32x32x16_bf16 v[84:99], v[186:189], v[128:131], v[84:99]
	s_nop 11
	v_max_f32_e64 v227, -v84, -v84
	v_max_f32_e64 v226, -v85, -v85
	v_max_f32_e64 v225, -v86, -v86
	v_max_f32_e64 v224, -v87, -v87
	v_max_f32_e64 v223, -v88, -v88
	v_max_f32_e64 v222, -v89, -v89
	v_max_f32_e64 v221, -v90, -v90
	v_max_f32_e64 v189, -v91, -v91
	v_max_f32_e64 v188, -v92, -v92
	v_max_f32_e64 v187, -v93, -v93
	v_max_f32_e64 v186, -v94, -v94
	v_max_f32_e64 v185, -v95, -v95
	v_max_f32_e64 v183, -v96, -v96
	v_max_f32_e64 v184, -v97, -v97
	v_max_f32_e64 v182, -v98, -v98
	v_max_f32_e64 v181, -v99, -v99
	s_cbranch_scc1 .LBB0_874
	v_min_f32_e32 v84, 0x42c80000, v227
	v_exp_f32_e32 v84, v84
	v_min_f32_e32 v85, 0x42c80000, v226
	v_exp_f32_e32 v85, v85
	v_or_b32_e32 v87, 32, v2
	v_add_f32_e32 v86, 1.0, v84
	v_rcp_f32_e32 v86, v86
	v_add_f32_e32 v88, 1.0, v85
	v_rcp_f32_e32 v88, v88
	v_min_f32_e32 v90, 0x42c80000, v224
	v_mul_f32_e32 v89, v84, v86
	v_cmp_lt_i32_e32 vcc, v87, v168
	v_exp_f32_e32 v90, v90
	v_mul_f32_e32 v87, v85, v88
	v_cndmask_b32_e32 v84, 0, v86, vcc
	v_cndmask_b32_e32 v86, 1.0, v89, vcc
	v_or_b32_e32 v89, 33, v2
	v_mov_b32_e32 v85, s45
	v_cmp_lt_i32_e32 vcc, v89, v168
	v_min_f32_e32 v91, 0x42c80000, v223
	v_exp_f32_e32 v93, v91
	v_cndmask_b32_e32 v85, v85, v88, vcc
	v_min_f32_e32 v88, 0x42c80000, v225
	v_exp_f32_e32 v92, v88
	v_add_f32_e32 v88, 1.0, v90
	v_rcp_f32_e32 v89, v88
	v_min_f32_e32 v91, 0x42c80000, v222
	v_exp_f32_e32 v91, v91
	v_cndmask_b32_e32 v88, 1.0, v87, vcc
	v_add_f32_e32 v87, 1.0, v92
	v_rcp_f32_e32 v96, v87
	v_mul_f32_e32 v87, v90, v89
	v_or_b32_e32 v90, 35, v2
	v_cmp_lt_i32_e32 vcc, v90, v168
	v_add_f32_e32 v90, 1.0, v91
	v_rcp_f32_e32 v95, v90
	v_min_f32_e32 v90, 0x42c80000, v221
	v_exp_f32_e32 v90, v90
	v_cndmask_b32_e32 v94, 1.0, v87, vcc
	v_add_f32_e32 v87, 1.0, v93
	v_rcp_f32_e32 v97, v87
	v_add_f32_e32 v98, 1.0, v90
	v_rcp_f32_e32 v99, v98
	v_min_f32_e32 v98, 0x42c80000, v189
	v_exp_f32_e32 v98, v98
	v_mul_f32_e32 v87, v91, v95
	v_or_b32_e32 v91, 41, v2
	v_cmp_lt_i32_e64 s[8:9], v91, v168
	v_min_f32_e32 v91, 0x42c80000, v188
	v_exp_f32_e32 v91, v91
	v_cndmask_b32_e64 v173, 1.0, v87, s[8:9]
	v_mul_f32_e32 v87, v90, v99
	v_add_f32_e32 v90, 1.0, v98
	v_rcp_f32_e32 v231, v90
	v_or_b32_e32 v90, 42, v2
	v_cmp_lt_i32_e64 s[10:11], v90, v168
	v_or_b32_e32 v90, 43, v2
	v_cmp_lt_i32_e64 s[12:13], v90, v168
	v_cndmask_b32_e64 v248, 1.0, v87, s[10:11]
	v_mul_f32_e32 v87, v98, v231
	v_cndmask_b32_e64 v249, 1.0, v87, s[12:13]
	v_min_f32_e32 v87, 0x42c80000, v187
	v_add_f32_e32 v90, 1.0, v91
	v_exp_f32_e32 v87, v87
	v_rcp_f32_e32 v242, v90
	v_or_b32_e32 v90, 48, v2
	v_cmp_lt_i32_e64 s[14:15], v90, v168
	v_add_f32_e32 v98, 1.0, v87
	v_mul_f32_e32 v91, v91, v242
	v_min_f32_e32 v90, 0x42c80000, v185
	v_min_f32_e32 v230, 0x42c80000, v184
	v_rcp_f32_e32 v243, v98
	v_cndmask_b32_e64 v98, 1.0, v91, s[14:15]
	v_exp_f32_e32 v91, v90
	v_exp_f32_e32 v232, v230
	v_min_f32_e32 v90, 0x42c80000, v186
	v_or_b32_e32 v229, 51, v2
	v_exp_f32_e32 v90, v90
	v_add_f32_e32 v228, 1.0, v91
	v_cmp_lt_i32_e64 s[20:21], v229, v168
	v_add_f32_e32 v229, 1.0, v232
	v_rcp_f32_e32 v244, v228
	v_rcp_f32_e32 v245, v229
	v_min_f32_e32 v229, 0x42c80000, v182
	v_or_b32_e32 v170, 49, v2
	v_exp_f32_e32 v233, v229
; __device__ __forceinline__ float fast_exp2(float x) { return __builtin_amdgcn_exp2f(x); }
; __device__ __forceinline__ float fast_rcp(float x) { return __builtin_amdgcn_rcpf(x); }
; template <int NB, bool MASK> __device__ __forceinline__ void sb_transform(f32x16* P, float& R, int hi, int kpos0, int qpos) {
;     float T[NB][4];
; #pragma unroll
;     for (int b = 0; b < NB; ++b)
; #pragma unroll
;         for (int g = 0; g < 4; ++g) {
;             float be[4], f[4];
; #pragma unroll
;             for (int i = 0; i < 4; ++i) {
;                 const float z = fmaxf(P[b][4 * g + i], -100.f);
;                 const float e = fast_exp2(-z), rc = fast_rcp(1.f + e);
;                 be[i] = rc; f[i] = e * rc;
;                 if (MASK) { const bool ok = (kpos0 + 32 * b + 8 * g + 4 * hi + i) < qpos; be[i] = ok ? be[i] : 0.f; f[i] = ok ? f[i] : 1.f; }
;             }
;             const float e2 = f[3], e1 = f[2] * f[3], e0 = f[1] * e1;
;             T[b][g] = f[0] * e0;
;             P[b][4 * g + 0] = be[0] * e0; P[b][4 * g + 1] = be[1] * e1; P[b][4 * g + 2] = be[2] * e2; P[b][4 * g + 3] = be[3];
;         }
;     float E = R;
; #pragma unroll
;     for (int b = NB - 1; b >= 0; --b)
; #pragma unroll
;         for (int g = 3; g >= 0; --g) {
;             const float To = __shfl_xor(T[b][g], 32);
;             const float Eg = hi ? E : E * To;
; #pragma unroll
;             for (int i = 0; i < 4; ++i) P[b][4 * g + i] *= Eg;
;             E = E * T[b][g] * To;
;         }
;     R = E;
; }
	v_mul_f32_e32 v87, v87, v243
	v_cmp_lt_i32_e64 s[16:17], v170, v168
	v_pk_mul_f32 v[92:93], v[92:93], v[96:97]
	v_add_f32_e32 v234, 1.0, v233
	v_cndmask_b32_e64 v170, 1.0, v87, s[16:17]
	v_add_f32_e32 v87, 1.0, v90
	v_rcp_f32_e32 v228, v87
	v_mul_f32_e32 v87, v91, v244
	v_min_f32_e32 v91, 0x42c80000, v183
	v_exp_f32_e32 v91, v91
	v_rcp_f32_e32 v246, v234
	v_min_f32_e32 v234, 0x42c80000, v181
	v_exp_f32_e32 v234, v234
	v_cndmask_b32_e64 v230, 1.0, v87, s[20:21]
	v_add_f32_e32 v87, 1.0, v91
	v_rcp_f32_e32 v229, v87
	v_mul_f32_e32 v87, v232, v245
	v_or_b32_e32 v232, 57, v2
	v_cmp_lt_i32_e64 s[26:27], v232, v168
	v_add_f32_e32 v232, 1.0, v234
	v_rcp_f32_e32 v250, v232
	v_or_b32_e32 v232, 58, v2
	v_cndmask_b32_e64 v247, 1.0, v87, s[26:27]
	v_mul_f32_e32 v87, v233, v246
	v_cmp_lt_i32_e64 s[22:23], v232, v168
	v_or_b32_e32 v232, 59, v2
	v_cmp_lt_i32_e64 s[18:19], v232, v168
	v_cndmask_b32_e64 v251, 1.0, v87, s[22:23]
	v_mul_f32_e32 v87, v234, v250
	v_cndmask_b32_e64 v252, 1.0, v87, s[18:19]
	v_xor_b32_e32 v87, 32, v191
	v_add_u32_e32 v232, 64, v192
	v_cmp_lt_i32_e64 s[28:29], v87, v232
	v_or_b32_e32 v232, 50, v2
	v_pk_mul_f32 v[90:91], v[90:91], v[228:229]
	v_cndmask_b32_e64 v87, v191, v87, s[28:29]
	v_lshlrev_b32_e32 v253, 2, v87
	v_or_b32_e32 v87, 56, v2
	v_cmp_lt_i32_e64 s[28:29], v87, v1
	v_or_b32_e32 v87, 34, v2
	v_cmp_lt_i32_e64 s[30:31], v232, v168
	v_cmp_lt_i32_e64 s[34:35], v87, v168
	v_cndmask_b32_e64 v233, 1.0, v91, s[28:29]
	v_cndmask_b32_e64 v232, 1.0, v90, s[30:31]
	v_cndmask_b32_e64 v90, 0, v96, s[34:35]
	v_or_b32_e32 v91, 40, v2
	v_mov_b32_e32 v87, s45
	v_mul_f32_e32 v234, v94, v90
	v_mov_b32_e32 v90, s45
	v_cndmask_b32_e32 v235, v87, v89, vcc
	v_cmp_lt_i32_e32 vcc, v91, v1
	v_cndmask_b32_e64 v90, v90, v99, s[10:11]
	v_mul_f32_e32 v91, v251, v252
	v_cndmask_b32_e64 v241, v87, v231, s[12:13]
	v_mul_f32_e32 v240, v249, v90
	v_mov_b32_e32 v90, s45
	v_mul_f32_e32 v231, v247, v91
	v_cndmask_b32_e64 v236, 1.0, v92, s[34:35]
	v_cndmask_b32_e64 v96, v90, v242, s[14:15]
	v_cndmask_b32_e64 v90, 0, v228, s[30:31]
	v_cndmask_b32_e64 v92, 0, v229, s[28:29]
	v_pk_mul_f32 v[228:229], v[232:233], v[230:231]
	v_mov_b32_e32 v99, v229
	v_mov_b32_e32 v255, v229
	s_nop 1
	v_permlane32_swap_b32_e32 v99, v255
	v_cndmask_b32_e64 v99, v99, v255, s[6:7]
	v_pk_mul_f32 v[232:233], v[170:171], v[228:229]
	v_cndmask_b32_e32 v237, 1.0, v93, vcc
	v_cndmask_b32_e32 v238, 0, v97, vcc
	v_cndmask_b32_e64 v97, v87, v243, s[16:17]
	v_cndmask_b32_e64 v243, v87, v244, s[20:21]
	v_cndmask_b32_e64 v93, v87, v245, s[26:27]
	s_waitcnt lgkmcnt(0)
	v_pk_mul_f32 v[244:245], v[98:99], v[232:233]
	v_mov_b32_e32 v89, v244
	v_mov_b32_e32 v255, v244
	s_nop 1
	v_permlane32_swap_b32_e32 v89, v255
	v_cndmask_b32_e64 v89, v89, v255, s[6:7]
	v_cndmask_b32_e64 v239, v87, v95, s[8:9]
	v_mul_f32_e32 v242, v230, v90
	v_mov_b32_e32 v90, s45
	v_cndmask_b32_e64 v247, v87, v250, s[18:19]
	v_mul_f32_e32 v87, v171, v99
	v_mul_f32_e32 v229, v248, v249
	v_cndmask_b32_e64 v90, v90, v246, s[22:23]
	v_cndmask_b32_e64 v98, v171, v87, s[6:7]
	s_waitcnt lgkmcnt(0)
	v_mul_f32_e32 v87, v245, v89
	v_mul_f32_e32 v95, v173, v229
	v_mul_f32_e32 v246, v252, v90
	v_cndmask_b32_e64 v170, v245, v87, s[6:7]
	v_mul_f32_e32 v87, v244, v245
	v_mov_b32_e32 v90, v231
	v_pk_mul_f32 v[230:231], v[236:237], v[94:95]
	v_mul_f32_e32 v89, v87, v89
	v_mov_b32_e32 v87, v231
	v_mov_b32_e32 v255, v231
	s_nop 1
	v_permlane32_swap_b32_e32 v87, v255
	v_cndmask_b32_e64 v87, v87, v255, s[6:7]
	v_mov_b32_e32 v233, v228
	v_pk_mul_f32 v[96:97], v[232:233], v[96:97]
	v_pk_mul_f32 v[232:233], v[88:89], v[230:231]
	v_mov_b32_e32 v228, v95
	v_pk_mul_f32 v[90:91], v[90:91], v[92:93]
	v_pk_mul_f32 v[94:95], v[228:229], v[238:239]
	s_waitcnt lgkmcnt(0)
	v_pk_mul_f32 v[228:229], v[86:87], v[232:233]
	v_pk_mul_f32 v[90:91], v[90:91], v[98:99] op_sel_hi:[1,0]
	v_pk_mul_f32 v[92:93], v[246:247], v[98:99] op_sel_hi:[1,0]
	v_pk_mul_f32 v[96:97], v[96:97], v[170:171] op_sel_hi:[1,0]
	v_pk_mul_f32 v[98:99], v[242:243], v[170:171] op_sel_hi:[1,0]
	v_mov_b32_e32 v170, v228
	v_mov_b32_e32 v255, v228
	s_nop 1
	v_permlane32_swap_b32_e32 v170, v255
	v_cndmask_b32_e64 v170, v170, v255, s[6:7]
	v_mul_f32_e32 v86, v89, v87
	v_cndmask_b32_e64 v86, v89, v86, s[6:7]
	v_pk_mul_f32 v[88:89], v[94:95], v[86:87] op_sel_hi:[1,0]
	v_mov_b32_e32 v233, v230
	s_waitcnt lgkmcnt(0)
	v_mul_f32_e32 v94, v229, v170
	v_cndmask_b32_e64 v94, v229, v94, s[6:7]
	v_pk_mul_f32 v[84:85], v[232:233], v[84:85]
	v_mul_f32_e32 v173, v228, v229
	v_pk_mul_f32 v[86:87], v[240:241], v[86:87] op_sel_hi:[1,0]
	v_pk_mul_f32 v[84:85], v[84:85], v[94:95] op_sel_hi:[1,0]
	v_pk_mul_f32 v[94:95], v[234:235], v[94:95] op_sel_hi:[1,0]
	v_mul_f32_e32 v173, v173, v170
	s_mov_b64 s[8:9], 0

; #define SBAR() __builtin_amdgcn_sched_barrier(0)
; template <int D0, int KS0> __device__ __forceinline__ void pv_one(f32x16& od, int vb, const bf16x8* pa) {
;     const s16x4 l0 = tr_read<v_rd_off(D0, KS0, 0)>(vb), h0 = tr_read<v_rd_off(D0, KS0, 1)>(vb), l1 = tr_read<v_rd_off(D0, KS0 + 1, 0)>(vb), h1 = tr_read<v_rd_off(D0, KS0 + 1, 1)>(vb);
;     asm volatile("s_waitcnt lgkmcnt(0)" ::: "memory"); SBAR();
;     od = __builtin_amdgcn_mfma_f32_32x32x16_bf16(pa[0], PKV(l0, h0), od, 0, 0, 0);
;     od = __builtin_amdgcn_mfma_f32_32x32x16_bf16(pa[1], PKV(l1, h1), od, 0, 0, 0);
; }
; template <int KS0> __device__ __forceinline__ void pv_blk(f32x16* o, int vb, const bf16x8* pa) {
;     pv_one<0, KS0>(o[0], vb, pa); pv_one<1, KS0>(o[1], vb, pa); pv_one<2, KS0>(o[2], vb, pa); pv_one<3, KS0>(o[3], vb, pa);
; }
; template <int MODE> ...
;     ...
;             ATT_BLOCK(1);
;             ATT_BLOCK(0);
.LBB0_876:
	v_cvt_pk_bf16_f32 v182, v84, v85
	v_cvt_pk_bf16_f32 v183, v94, v95
	v_cvt_pk_bf16_f32 v184, v88, v89
	v_cvt_pk_bf16_f32 v185, v86, v87
	v_cvt_pk_bf16_f32 v234, v96, v97
	v_cvt_pk_bf16_f32 v235, v98, v99
	v_cvt_pk_bf16_f32 v236, v90, v91
	v_cvt_pk_bf16_f32 v237, v92, v93
	s_nop 0
	v_permlane32_swap_b32_e32 v182, v184
	v_permlane32_swap_b32_e32 v183, v185
	v_permlane32_swap_b32_e32 v234, v236
	v_permlane32_swap_b32_e32 v235, v237
	v_add_u32_e32 v170, s87, v220
	ds_read_b64_tr_b16 v[84:85], v170 offset:8192
	ds_read_b64_tr_b16 v[86:87], v170 offset:10240
	ds_read_b64_tr_b16 v[88:89], v170 offset:12288
	ds_read_b64_tr_b16 v[90:91], v170 offset:14336
	ds_read_b64_tr_b16 v[92:93], v170 offset:8704
	ds_read_b64_tr_b16 v[94:95], v170 offset:10752
	ds_read_b64_tr_b16 v[96:97], v170 offset:12800
	ds_read_b64_tr_b16 v[98:99], v170 offset:14848
	ds_read_b64_tr_b16 v[238:239], v170 offset:9216
	ds_read_b64_tr_b16 v[240:241], v170 offset:11264
	ds_read_b64_tr_b16 v[242:243], v170 offset:13312
	ds_read_b64_tr_b16 v[244:245], v170 offset:15360
	ds_read_b64_tr_b16 v[246:247], v170 offset:9728
	ds_read_b64_tr_b16 v[248:249], v170 offset:11776
	ds_read_b64_tr_b16 v[250:251], v170 offset:13824
	ds_read_b64_tr_b16 v[252:253], v170 offset:15872
	s_waitcnt lgkmcnt(14)
	v_mfma_f32_32x32x16_bf16 v[52:67], v[182:185], v[84:87], v[52:67]
	s_waitcnt lgkmcnt(12)
	v_mfma_f32_32x32x16_bf16 v[52:67], v[234:237], v[88:91], v[52:67]
	s_waitcnt lgkmcnt(10)
	v_mfma_f32_32x32x16_bf16 v[36:51], v[182:185], v[92:95], v[36:51]
	s_waitcnt lgkmcnt(8)
	v_mfma_f32_32x32x16_bf16 v[36:51], v[234:237], v[96:99], v[36:51]
	s_waitcnt lgkmcnt(6)
	v_mfma_f32_32x32x16_bf16 v[20:35], v[182:185], v[238:241], v[20:35]
	s_waitcnt lgkmcnt(4)
	v_mfma_f32_32x32x16_bf16 v[20:35], v[234:237], v[242:245], v[20:35]
	s_waitcnt lgkmcnt(2)
	v_mfma_f32_32x32x16_bf16 v[4:19], v[182:185], v[246:249], v[4:19]
	s_waitcnt lgkmcnt(0)
	v_mfma_f32_32x32x16_bf16 v[4:19], v[234:237], v[250:253], v[4:19]
	ds_read_b128 v[222:225], v172 offset:32768
	ds_read_b128 v[226:229], v174 offset:32768
	ds_read_b128 v[230:233], v175 offset:32768
	ds_read_b128 v[238:241], v176 offset:32768
	ds_read_b128 v[242:245], v177 offset:32768
	ds_read_b128 v[246:249], v178 offset:32768
	ds_read_b128 v[250:253], v179 offset:32768
	ds_read_b128 v[186:189], v180 offset:32768
	s_mov_b64 s[8:9], -1
	s_andn2_b64 vcc, exec, s[50:51]
	s_waitcnt lgkmcnt(7)
	v_mfma_f32_32x32x16_bf16 v[84:99], v[222:225], v[100:103], v[68:83]
	s_waitcnt lgkmcnt(6)
	v_mfma_f32_32x32x16_bf16 v[84:99], v[226:229], v[104:107], v[84:99]
	s_waitcnt lgkmcnt(5)
	v_mfma_f32_32x32x16_bf16 v[84:99], v[230:233], v[108:111], v[84:99]
	s_waitcnt lgkmcnt(4)
	v_mfma_f32_32x32x16_bf16 v[84:99], v[238:241], v[112:115], v[84:99]
	s_waitcnt lgkmcnt(3)
	v_mfma_f32_32x32x16_bf16 v[84:99], v[242:245], v[116:119], v[84:99]
	s_waitcnt lgkmcnt(2)
	v_mfma_f32_32x32x16_bf16 v[84:99], v[246:249], v[120:123], v[84:99]
	s_waitcnt lgkmcnt(1)
	v_mfma_f32_32x32x16_bf16 v[84:99], v[250:253], v[124:127], v[84:99]
	s_waitcnt lgkmcnt(0)
	v_mfma_f32_32x32x16_bf16 v[84:99], v[186:189], v[128:131], v[84:99]
	s_nop 11
	v_max_f32_e64 v232, -v84, -v84
	v_max_f32_e64 v231, -v85, -v85
	v_max_f32_e64 v230, -v86, -v86
	v_max_f32_e64 v229, -v87, -v87
	v_max_f32_e64 v228, -v88, -v88
	v_max_f32_e64 v227, -v89, -v89
	v_max_f32_e64 v226, -v90, -v90
	v_max_f32_e64 v225, -v91, -v91
	v_max_f32_e64 v224, -v92, -v92
	v_max_f32_e64 v223, -v93, -v93
	v_max_f32_e64 v222, -v94, -v94
	v_max_f32_e64 v221, -v95, -v95
	v_max_f32_e64 v94, -v96, -v96
	v_max_f32_e64 v95, -v97, -v97
	v_max_f32_e64 v93, -v98, -v98
	v_max_f32_e64 v92, -v99, -v99
	s_cbranch_vccnz .LBB0_878
	v_min_f32_e32 v84, 0x42c80000, v232
	v_exp_f32_e32 v84, v84
	v_min_f32_e32 v85, 0x42c80000, v231
	v_exp_f32_e32 v85, v85
	v_min_f32_e32 v91, 0x42c80000, v228
	v_add_f32_e32 v86, 1.0, v84
	v_rcp_f32_e32 v86, v86
	v_add_f32_e32 v87, 1.0, v85
	v_exp_f32_e32 v97, v91
	v_min_f32_e32 v91, 0x42c80000, v227
	v_rcp_f32_e32 v87, v87
	v_exp_f32_e32 v91, v91
	v_min_f32_e32 v90, 0x42c80000, v229
	v_exp_f32_e32 v90, v90
	v_mul_f32_e32 v88, v84, v86
	v_cmp_lt_i32_e32 vcc, v2, v168
	v_or_b32_e32 v89, 1, v2
	v_add_f32_e32 v99, 1.0, v91
	v_cndmask_b32_e32 v84, 0, v86, vcc
	v_cndmask_b32_e32 v86, 1.0, v88, vcc
	v_mul_f32_e32 v88, v85, v87
	v_mov_b32_e32 v85, s45
	v_cmp_lt_i32_e32 vcc, v89, v168
	v_rcp_f32_e32 v171, v99
	v_min_f32_e32 v99, 0x42c80000, v226
	v_cndmask_b32_e32 v85, v85, v87, vcc
	v_min_f32_e32 v87, 0x42c80000, v230
	v_exp_f32_e32 v96, v87
	v_add_f32_e32 v87, 1.0, v90
	v_exp_f32_e32 v172, v99
	v_rcp_f32_e32 v89, v87
	v_add_f32_e32 v87, 1.0, v96
	v_rcp_f32_e32 v98, v87
	v_add_f32_e32 v174, 1.0, v172
	v_mul_f32_e32 v87, v90, v89
	v_or_b32_e32 v90, 3, v2
	v_rcp_f32_e32 v175, v174
	v_min_f32_e32 v174, 0x42c80000, v225
	v_cndmask_b32_e32 v88, 1.0, v88, vcc
	v_cmp_lt_i32_e32 vcc, v90, v168
	v_exp_f32_e32 v174, v174
	v_min_f32_e32 v180, 0x42c80000, v95
	v_cndmask_b32_e32 v90, 1.0, v87, vcc
	v_add_f32_e32 v87, 1.0, v97
	v_rcp_f32_e32 v99, v87
	v_mul_f32_e32 v87, v91, v171
	v_or_b32_e32 v91, 9, v2
	v_cmp_lt_i32_e64 s[8:9], v91, v168
	v_exp_f32_e32 v182, v180
	v_or_b32_e32 v179, 19, v2
	v_cndmask_b32_e64 v91, 1.0, v87, s[8:9]
	v_mul_f32_e32 v87, v172, v175
	v_add_f32_e32 v172, 1.0, v174
	v_rcp_f32_e32 v181, v172
	v_or_b32_e32 v172, 10, v2
	v_cmp_lt_i32_e64 s[10:11], v172, v168
	v_or_b32_e32 v172, 11, v2
	v_cmp_lt_i32_e64 s[12:13], v172, v168
	v_cndmask_b32_e64 v233, 1.0, v87, s[10:11]
	v_mul_f32_e32 v87, v174, v181
; __device__ __forceinline__ float fast_exp2(float x) { return __builtin_amdgcn_exp2f(x); }
; __device__ __forceinline__ float fast_rcp(float x) { return __builtin_amdgcn_rcpf(x); }
; template <int NB, bool MASK> __device__ __forceinline__ void sb_transform(f32x16* P, float& R, int hi, int kpos0, int qpos) {
;     float T[NB][4];
; #pragma unroll
;     for (int b = 0; b < NB; ++b)
; #pragma unroll
;         for (int g = 0; g < 4; ++g) {
;             float be[4], f[4];
; #pragma unroll
;             for (int i = 0; i < 4; ++i) {
;                 const float z = fmaxf(P[b][4 * g + i], -100.f);
;                 const float e = fast_exp2(-z), rc = fast_rcp(1.f + e);
;                 be[i] = rc; f[i] = e * rc;
;                 if (MASK) { const bool ok = (kpos0 + 32 * b + 8 * g + 4 * hi + i) < qpos; be[i] = ok ? be[i] : 0.f; f[i] = ok ? f[i] : 1.f; }
;             }
;             const float e2 = f[3], e1 = f[2] * f[3], e0 = f[1] * e1;
;             T[b][g] = f[0] * e0;
;             P[b][4 * g + 0] = be[0] * e0; P[b][4 * g + 1] = be[1] * e1; P[b][4 * g + 2] = be[2] * e2; P[b][4 * g + 3] = be[3];
;         }
;     float E = R;
; #pragma unroll
;     for (int b = NB - 1; b >= 0; --b)
; #pragma unroll
;         for (int g = 3; g >= 0; --g) {
;             const float To = __shfl_xor(T[b][g], 32);
;             const float Eg = hi ? E : E * To;
; #pragma unroll
;             for (int i = 0; i < 4; ++i) P[b][4 * g + i] *= Eg;
;             E = E * T[b][g] * To;
;         }
;     R = E;
; }
	v_min_f32_e32 v174, 0x42c80000, v224
	v_exp_f32_e32 v174, v174
	v_cndmask_b32_e64 v242, 1.0, v87, s[12:13]
	v_min_f32_e32 v87, 0x42c80000, v223
	v_exp_f32_e32 v87, v87
	v_add_f32_e32 v172, 1.0, v174
	v_rcp_f32_e32 v184, v172
	v_or_b32_e32 v172, 16, v2
	v_cmp_lt_i32_e64 s[14:15], v172, v168
	v_min_f32_e32 v172, 0x42c80000, v221
	v_exp_f32_e32 v177, v172
	v_add_f32_e32 v176, 1.0, v87
	v_rcp_f32_e32 v185, v176
	v_min_f32_e32 v176, 0x42c80000, v222
	v_exp_f32_e32 v176, v176
	v_add_f32_e32 v178, 1.0, v177
	v_cmp_lt_i32_e64 s[20:21], v179, v168
	v_add_f32_e32 v179, 1.0, v182
	v_rcp_f32_e32 v186, v178
	v_rcp_f32_e32 v234, v179
	v_min_f32_e32 v179, 0x42c80000, v93
	v_or_b32_e32 v172, 17, v2
	v_exp_f32_e32 v183, v179
	v_mul_f32_e32 v87, v87, v185
	v_cmp_lt_i32_e64 s[16:17], v172, v168
	v_mul_f32_e32 v174, v174, v184
	v_add_f32_e32 v187, 1.0, v183
	v_cndmask_b32_e64 v172, 1.0, v87, s[16:17]
	v_add_f32_e32 v87, 1.0, v176
	v_rcp_f32_e32 v178, v87
	v_mul_f32_e32 v87, v177, v186
	v_min_f32_e32 v177, 0x42c80000, v94
	v_exp_f32_e32 v177, v177
	v_rcp_f32_e32 v238, v187
	v_min_f32_e32 v187, 0x42c80000, v92
	v_exp_f32_e32 v187, v187
	v_cndmask_b32_e64 v180, 1.0, v87, s[20:21]
	v_add_f32_e32 v87, 1.0, v177
	v_rcp_f32_e32 v179, v87
	v_mul_f32_e32 v87, v182, v234
	v_or_b32_e32 v182, 25, v2
	v_cmp_lt_i32_e64 s[26:27], v182, v168
	v_add_f32_e32 v182, 1.0, v187
	v_rcp_f32_e32 v240, v182
	v_or_b32_e32 v182, 26, v2
	v_cndmask_b32_e64 v236, 1.0, v87, s[26:27]
	v_mul_f32_e32 v87, v183, v238
	v_cmp_lt_i32_e64 s[22:23], v182, v168
	v_or_b32_e32 v182, 27, v2
	v_cmp_lt_i32_e64 s[18:19], v182, v168
	v_cndmask_b32_e64 v235, 1.0, v87, s[22:23]
	v_mul_f32_e32 v87, v187, v240
	v_cndmask_b32_e64 v243, 1.0, v87, s[18:19]
	v_xor_b32_e32 v87, 32, v191
	v_add_u32_e32 v182, 64, v192
	v_cmp_lt_i32_e64 s[28:29], v87, v182
	v_or_b32_e32 v182, 18, v2
	v_cmp_lt_i32_e64 s[30:31], v182, v168
	v_cndmask_b32_e64 v87, v191, v87, s[28:29]
	v_lshlrev_b32_e32 v244, 2, v87
	v_or_b32_e32 v87, 24, v2
	v_or_b32_e32 v182, 8, v2
	v_or_b32_e32 v2, 2, v2
	v_pk_mul_f32 v[176:177], v[176:177], v[178:179]
	v_cmp_lt_i32_e64 s[28:29], v87, v1
	v_cmp_lt_i32_e64 s[34:35], v2, v168
	v_mov_b32_e32 v87, s45
	v_mul_f32_e32 v235, v235, v243
	v_cndmask_b32_e64 v177, 1.0, v177, s[28:29]
	v_cndmask_b32_e64 v176, 1.0, v176, s[30:31]
	v_cndmask_b32_e64 v2, 0, v98, s[34:35]
	v_cndmask_b32_e64 v183, v87, v181, s[12:13]
	v_mul_f32_e32 v181, v236, v235
	v_mul_f32_e32 v188, v90, v2
	v_mov_b32_e32 v2, s45
	v_pk_mul_f32 v[236:237], v[176:177], v[180:181]
	v_cndmask_b32_e64 v2, v2, v175, s[10:11]
	v_mov_b32_e32 v175, v237
	v_mov_b32_e32 v255, v237
	s_nop 1
	v_permlane32_swap_b32_e32 v175, v255
	v_cndmask_b32_e64 v175, v175, v255, s[6:7]
	v_cndmask_b32_e32 v189, v87, v89, vcc
	v_cmp_lt_i32_e32 vcc, v182, v1
	v_mul_f32_e32 v182, v242, v2
	v_mov_b32_e32 v2, s45
	v_cndmask_b32_e64 v184, v2, v184, s[14:15]
	v_cndmask_b32_e64 v2, 0, v178, s[30:31]
	v_cndmask_b32_e64 v187, v87, v186, s[20:21]
	v_mul_f32_e32 v186, v180, v2
	v_mov_b32_e32 v2, s45
	v_cndmask_b32_e64 v174, 1.0, v174, s[14:15]
	v_cndmask_b32_e64 v2, v2, v238, s[22:23]
	v_pk_mul_f32 v[238:239], v[172:173], v[236:237]
	v_cndmask_b32_e64 v185, v87, v185, s[16:17]
	s_waitcnt lgkmcnt(0)
	v_pk_mul_f32 v[176:177], v[174:175], v[238:239]
	v_mov_b32_e32 v89, v176
	v_mov_b32_e32 v255, v176
	s_nop 1
	v_permlane32_swap_b32_e32 v89, v255
	v_cndmask_b32_e64 v89, v89, v255, s[6:7]
	v_cndmask_b32_e64 v178, 0, v179, s[28:29]
	v_cndmask_b32_e64 v179, v87, v234, s[26:27]
	v_mov_b32_e32 v234, v181
	v_mov_b32_e32 v239, v236
	v_pk_mul_f32 v[96:97], v[96:97], v[98:99]
	v_cndmask_b32_e64 v241, v87, v240, s[18:19]
	v_mul_f32_e32 v240, v243, v2
	v_mul_f32_e32 v2, v173, v175
	v_pk_mul_f32 v[174:175], v[234:235], v[178:179]
	v_pk_mul_f32 v[178:179], v[238:239], v[184:185]
	v_mul_f32_e32 v185, v233, v242
	v_cndmask_b32_e32 v97, 1.0, v97, vcc
	v_cndmask_b32_e64 v96, 1.0, v96, s[34:35]
	v_cndmask_b32_e32 v98, 0, v99, vcc
	v_cndmask_b32_e64 v99, v87, v171, s[8:9]
	s_waitcnt lgkmcnt(0)
	v_mul_f32_e32 v87, v177, v89
	v_mul_f32_e32 v91, v91, v185
	v_cndmask_b32_e64 v172, v177, v87, s[6:7]
	v_mul_f32_e32 v87, v176, v177
	v_pk_mul_f32 v[96:97], v[96:97], v[90:91]
	v_mul_f32_e32 v89, v87, v89
	v_mov_b32_e32 v87, v97
	v_mov_b32_e32 v255, v97
	s_nop 1
	v_permlane32_swap_b32_e32 v87, v255
	v_cndmask_b32_e64 v87, v87, v255, s[6:7]
	v_pk_mul_f32 v[180:181], v[186:187], v[172:173] op_sel_hi:[1,0]
	v_pk_mul_f32 v[186:187], v[88:89], v[96:97]
	v_mov_b32_e32 v184, v91
	v_pk_mul_f32 v[90:91], v[184:185], v[98:99]
	s_waitcnt lgkmcnt(0)
	v_pk_mul_f32 v[98:99], v[86:87], v[186:187]
	v_mov_b32_e32 v86, v98
	v_mov_b32_e32 v255, v98
	s_nop 1
	v_permlane32_swap_b32_e32 v86, v255
	v_cndmask_b32_e64 v86, v86, v255, s[6:7]
	v_cndmask_b32_e64 v2, v173, v2, s[6:7]
	v_pk_mul_f32 v[176:177], v[174:175], v[2:3] op_sel_hi:[1,0]
	v_pk_mul_f32 v[174:175], v[240:241], v[2:3] op_sel_hi:[1,0]
	v_mul_f32_e32 v2, v89, v87
	v_cndmask_b32_e64 v2, v89, v2, s[6:7]
	v_pk_mul_f32 v[184:185], v[90:91], v[2:3] op_sel_hi:[1,0]
	v_pk_mul_f32 v[182:183], v[182:183], v[2:3] op_sel_hi:[1,0]
	s_waitcnt lgkmcnt(0)
	v_mul_f32_e32 v2, v99, v86
	v_mov_b32_e32 v187, v96
	v_cndmask_b32_e64 v2, v99, v2, s[6:7]
	v_pk_mul_f32 v[84:85], v[186:187], v[84:85]
	v_pk_mul_f32 v[188:189], v[188:189], v[2:3] op_sel_hi:[1,0]
	v_pk_mul_f32 v[186:187], v[84:85], v[2:3] op_sel_hi:[1,0]
	v_mul_f32_e32 v2, v98, v99
	v_pk_mul_f32 v[178:179], v[178:179], v[172:173] op_sel_hi:[1,0]
	v_mul_f32_e32 v171, v2, v86
	s_mov_b64 s[8:9], 0

; #define SBAR() __builtin_amdgcn_sched_barrier(0)
; template <int D0, int KS0> __device__ __forceinline__ void pv_one(f32x16& od, int vb, const bf16x8* pa) {
;     const s16x4 l0 = tr_read<v_rd_off(D0, KS0, 0)>(vb), h0 = tr_read<v_rd_off(D0, KS0, 1)>(vb), l1 = tr_read<v_rd_off(D0, KS0 + 1, 0)>(vb), h1 = tr_read<v_rd_off(D0, KS0 + 1, 1)>(vb);
;     asm volatile("s_waitcnt lgkmcnt(0)" ::: "memory"); SBAR();
;     od = __builtin_amdgcn_mfma_f32_32x32x16_bf16(pa[0], PKV(l0, h0), od, 0, 0, 0);
;     od = __builtin_amdgcn_mfma_f32_32x32x16_bf16(pa[1], PKV(l1, h1), od, 0, 0, 0);
; }
; template <int KS0> __device__ __forceinline__ void pv_blk(f32x16* o, int vb, const bf16x8* pa) {
;     pv_one<0, KS0>(o[0], vb, pa); pv_one<1, KS0>(o[1], vb, pa); pv_one<2, KS0>(o[2], vb, pa); pv_one<3, KS0>(o[3], vb, pa);
; }
; __device__ __forceinline__ void pack_p(const f32x16& P, bf16x8& out0, bf16x8& out1) {
;     ...
;     PK4(0, out0); PK4(8, out1);
;     ...
; }
.LBB0_880:
	v_cvt_pk_bf16_f32 v84, v186, v187
	v_cvt_pk_bf16_f32 v85, v188, v189
	v_cvt_pk_bf16_f32 v86, v184, v185
	v_cvt_pk_bf16_f32 v87, v182, v183
	v_cvt_pk_bf16_f32 v88, v178, v179
	v_cvt_pk_bf16_f32 v89, v180, v181
	v_cvt_pk_bf16_f32 v90, v176, v177
	v_cvt_pk_bf16_f32 v91, v174, v175
	s_nop 0
	v_permlane32_swap_b32_e32 v84, v86
	v_permlane32_swap_b32_e32 v85, v87
	v_permlane32_swap_b32_e32 v88, v90
	v_permlane32_swap_b32_e32 v89, v91
	ds_read_b64_tr_b16 v[92:93], v170 offset:0
	ds_read_b64_tr_b16 v[94:95], v170 offset:2048
	ds_read_b64_tr_b16 v[96:97], v170 offset:4096
	ds_read_b64_tr_b16 v[98:99], v170 offset:6144
	ds_read_b64_tr_b16 v[172:173], v170 offset:512
	ds_read_b64_tr_b16 v[174:175], v170 offset:2560
	ds_read_b64_tr_b16 v[176:177], v170 offset:4608
	ds_read_b64_tr_b16 v[178:179], v170 offset:6656
	ds_read_b64_tr_b16 v[180:181], v170 offset:1024
	ds_read_b64_tr_b16 v[182:183], v170 offset:3072
	ds_read_b64_tr_b16 v[184:185], v170 offset:5120
	ds_read_b64_tr_b16 v[186:187], v170 offset:7168
	ds_read_b64_tr_b16 v[222:223], v170 offset:1536
	ds_read_b64_tr_b16 v[224:225], v170 offset:3584
	ds_read_b64_tr_b16 v[226:227], v170 offset:5632
	ds_read_b64_tr_b16 v[228:229], v170 offset:7680
	s_waitcnt lgkmcnt(14)
	v_mfma_f32_32x32x16_bf16 v[52:67], v[84:87], v[92:95], v[52:67]
	s_waitcnt lgkmcnt(12)
	v_mfma_f32_32x32x16_bf16 v[52:67], v[88:91], v[96:99], v[52:67]
	s_waitcnt lgkmcnt(10)
	v_mfma_f32_32x32x16_bf16 v[36:51], v[84:87], v[172:175], v[36:51]
	s_waitcnt lgkmcnt(8)
	v_mfma_f32_32x32x16_bf16 v[36:51], v[88:91], v[176:179], v[36:51]
	s_waitcnt lgkmcnt(6)
	v_mfma_f32_32x32x16_bf16 v[20:35], v[84:87], v[180:183], v[20:35]
	s_waitcnt lgkmcnt(4)
	v_mfma_f32_32x32x16_bf16 v[20:35], v[88:91], v[184:187], v[20:35]
	s_waitcnt lgkmcnt(2)
	v_mfma_f32_32x32x16_bf16 v[4:19], v[84:87], v[222:225], v[4:19]
	s_waitcnt lgkmcnt(0)
	v_mfma_f32_32x32x16_bf16 v[4:19], v[88:91], v[226:229], v[4:19]
	s_andn2_b64 vcc, exec, s[46:47]
	s_cbranch_vccz .LBB0_863
	s_branch .LBB0_864
